# attention: softmax finish of keys 32..63 issued between the PV MFMAs of k-slices 0,1 (on top of QK prefetch and PEER U pipelining)
# speedup vs baseline: 1.0192x; 1.0045x over previous
; #define SBAR() __builtin_amdgcn_sched_barrier(0)
; __device__ __forceinline__ void partialSM(f32x16& p0, f32x16& p1, float& m_reg, float& mn, float& alpha, int rem, int hi) {
;     ...
;   else { mn = fmaxf(m_reg, pmax); alpha = __builtin_amdgcn_exp2f((m_reg - mn) * C); m_reg = mn; }
;   float mnC = -mn * C;
; #pragma unroll
;   for (int r = 0; r < 16; ++r) p0[r] = fmaf(p0[r], C, mnC);
; #pragma unroll
;   for (int r = 0; r < 16; ++r) p1[r] = fmaf(p1[r], C, mnC);
; #pragma unroll
;   for (int r = 0; r < 16; ++r) p0[r] = __builtin_amdgcn_exp2f(p0[r]);
; }
; __device__ __forceinline__ void finishSM(f32x16& p0, f32x16& p1, float alpha, float& l_reg, bf16x8& pa0, bf16x8& pa1, bf16x8& pa2, bf16x8& pa3) {
; #pragma unroll
;   for (int r = 0; r < 16; ++r) p1[r] = __builtin_amdgcn_exp2f(p1[r]);
;   float ps = 0;
; #pragma unroll
;   for (int r = 0; r < 16; ++r) ps += p0[r];
; #pragma unroll
;   for (int r = 0; r < 16; ++r) ps += p1[r];
;   { auto rr = __builtin_amdgcn_permlane32_swap(__float_as_uint(ps), __float_as_uint(ps), false, false);
;     ps = __uint_as_float(rr[0]) + __uint_as_float(rr[1]); }
;   l_reg = l_reg * alpha + ps;
;     ...
;   PK4(p0, 0, pa0); PK4(p0, 8, pa1); PK4(p1, 0, pa2); PK4(p1, 8, pa3);
;     ...
; }
; template <int D0> __device__ __forceinline__ void pv_one8(f32x16& od, int vb, bf16x8 pa0, bf16x8 pa1, bf16x8 pa2, bf16x8 pa3) {
;   constexpr int HB = (D0 >> 2) * 16384, DD = D0 & 3;
;   const s16x4 l0 = tr_read<HB + v_rd_off(DD, 0, 0)>(vb), h0 = tr_read<HB + v_rd_off(DD, 0, 1)>(vb), l1 = tr_read<HB + v_rd_off(DD, 1, 0)>(vb), h1 = tr_read<HB + v_rd_off(DD, 1, 1)>(vb);
;   const s16x4 l2 = tr_read<HB + v_rd_off(DD, 2, 0)>(vb), h2 = tr_read<HB + v_rd_off(DD, 2, 1)>(vb), l3 = tr_read<HB + v_rd_off(DD, 3, 0)>(vb), h3 = tr_read<HB + v_rd_off(DD, 3, 1)>(vb);
;   asm volatile("s_waitcnt lgkmcnt(0)" ::: "memory"); SBAR();
;     ...
;   od = __builtin_amdgcn_mfma_f32_32x32x16_bf16(pa0, PK(l0, h0), od, 0, 0, 0);
;   od = __builtin_amdgcn_mfma_f32_32x32x16_bf16(pa1, PK(l1, h1), od, 0, 0, 0);
;   od = __builtin_amdgcn_mfma_f32_32x32x16_bf16(pa2, PK(l2, h2), od, 0, 0, 0);
;   od = __builtin_amdgcn_mfma_f32_32x32x16_bf16(pa3, PK(l3, h3), od, 0, 0, 0);
.LBB0_937:
	v_cndmask_b32_e64 v246, v248, v246, s[4:5]
	v_mul_f32_e32 v194, 0xbe0293ee, v246
	v_fmamk_f32 v146, v146, 0x3e0293ee, v194
	v_fmamk_f32 v147, v147, 0x3e0293ee, v194
	v_fmamk_f32 v148, v148, 0x3e0293ee, v194
	v_fmamk_f32 v149, v149, 0x3e0293ee, v194
	v_fmamk_f32 v150, v150, 0x3e0293ee, v194
	v_fmamk_f32 v151, v151, 0x3e0293ee, v194
	v_fmamk_f32 v152, v152, 0x3e0293ee, v194
	v_fmamk_f32 v153, v153, 0x3e0293ee, v194
	v_fmamk_f32 v154, v154, 0x3e0293ee, v194
	v_fmamk_f32 v155, v155, 0x3e0293ee, v194
	v_fmamk_f32 v156, v156, 0x3e0293ee, v194
	v_fmamk_f32 v157, v157, 0x3e0293ee, v194
	v_fmamk_f32 v158, v158, 0x3e0293ee, v194
	v_fmamk_f32 v159, v159, 0x3e0293ee, v194
	v_fmamk_f32 v160, v160, 0x3e0293ee, v194
	v_fmamk_f32 v161, v161, 0x3e0293ee, v194
	v_exp_f32_e32 v146, v146
	v_exp_f32_e32 v147, v147
	v_exp_f32_e32 v148, v148
	v_exp_f32_e32 v149, v149
	v_exp_f32_e32 v150, v150
	v_exp_f32_e32 v151, v151
	v_exp_f32_e32 v152, v152
	v_exp_f32_e32 v153, v153
	v_exp_f32_e32 v154, v154
	v_exp_f32_e32 v155, v155
	v_exp_f32_e32 v156, v156
	v_exp_f32_e32 v157, v157
	v_exp_f32_e32 v158, v158
	v_exp_f32_e32 v159, v159
	v_exp_f32_e32 v160, v160
	v_exp_f32_e32 v161, v161
	s_add_i32 s29, s29, 0x8000
	v_add_f32_e32 v205, v146, v147
	v_add_f32_e32 v206, v148, v149
	v_add_f32_e32 v205, v150, v205
	v_add_f32_e32 v206, v151, v206
	v_add_f32_e32 v205, v152, v205
	v_add_f32_e32 v206, v153, v206
	v_add_f32_e32 v205, v154, v205
	v_add_f32_e32 v206, v155, v206
	v_add_f32_e32 v205, v156, v205
	v_add_f32_e32 v206, v157, v206
	v_add_f32_e32 v205, v158, v205
	v_add_f32_e32 v206, v159, v206
	v_add_f32_e32 v205, v160, v205
	v_add_f32_e32 v206, v161, v206
	v_add_f32_e32 v205, v206, v205
	v_cvt_pk_bf16_f32 v196, v146, v147
	v_cvt_pk_bf16_f32 v197, v148, v149
	v_cvt_pk_bf16_f32 v198, v150, v151
	v_cvt_pk_bf16_f32 v199, v152, v153
	v_cvt_pk_bf16_f32 v200, v154, v155
	v_cvt_pk_bf16_f32 v201, v156, v157
	v_cvt_pk_bf16_f32 v202, v158, v159
	v_cvt_pk_bf16_f32 v203, v160, v161
	v_add_u32_e32 v195, s29, v235
	s_nop 0
	v_permlane32_swap_b32_e32 v196, v198
	v_permlane32_swap_b32_e32 v197, v199
	v_permlane32_swap_b32_e32 v200, v202
	v_permlane32_swap_b32_e32 v201, v203
	ds_read_b64_tr_b16 v[146:147], v195 offset:0
	ds_read_b64_tr_b16 v[148:149], v195 offset:2048
	ds_read_b64_tr_b16 v[150:151], v195 offset:4096
	ds_read_b64_tr_b16 v[152:153], v195 offset:6144
	ds_read_b64_tr_b16 v[154:155], v195 offset:512
	ds_read_b64_tr_b16 v[156:157], v195 offset:2560
	ds_read_b64_tr_b16 v[158:159], v195 offset:4608
	ds_read_b64_tr_b16 v[160:161], v195 offset:6656
	s_waitcnt lgkmcnt(4)
	v_mfma_f32_32x32x16_bf16 v[114:129], v[196:199], v[146:149], v[114:129]
	v_fmamk_f32 v130, v130, 0x3e0293ee, v194
	v_fmamk_f32 v131, v131, 0x3e0293ee, v194
	v_fmamk_f32 v132, v132, 0x3e0293ee, v194
	v_fmamk_f32 v133, v133, 0x3e0293ee, v194
	v_mfma_f32_32x32x16_bf16 v[114:129], v[200:203], v[150:153], v[114:129]
	v_fmamk_f32 v134, v134, 0x3e0293ee, v194
	v_fmamk_f32 v135, v135, 0x3e0293ee, v194
	v_fmamk_f32 v136, v136, 0x3e0293ee, v194
	v_fmamk_f32 v137, v137, 0x3e0293ee, v194
	ds_read_b64_tr_b16 v[146:147], v195 offset:1024
	ds_read_b64_tr_b16 v[148:149], v195 offset:3072
	ds_read_b64_tr_b16 v[150:151], v195 offset:5120
	ds_read_b64_tr_b16 v[152:153], v195 offset:7168
	s_waitcnt lgkmcnt(4)
	v_mfma_f32_32x32x16_bf16 v[98:113], v[196:199], v[154:157], v[98:113]
	v_fmamk_f32 v138, v138, 0x3e0293ee, v194
	v_fmamk_f32 v139, v139, 0x3e0293ee, v194
	v_fmamk_f32 v140, v140, 0x3e0293ee, v194
	v_fmamk_f32 v141, v141, 0x3e0293ee, v194
	v_mfma_f32_32x32x16_bf16 v[98:113], v[200:203], v[158:161], v[98:113]
	v_fmamk_f32 v142, v142, 0x3e0293ee, v194
	v_fmamk_f32 v143, v143, 0x3e0293ee, v194
	v_fmamk_f32 v144, v144, 0x3e0293ee, v194
	v_fmamk_f32 v145, v145, 0x3e0293ee, v194
	ds_read_b64_tr_b16 v[154:155], v195 offset:1536
	ds_read_b64_tr_b16 v[156:157], v195 offset:3584
	ds_read_b64_tr_b16 v[158:159], v195 offset:5632
	ds_read_b64_tr_b16 v[160:161], v195 offset:7680
	s_waitcnt lgkmcnt(4)
	v_mfma_f32_32x32x16_bf16 v[82:97], v[196:199], v[146:149], v[82:97]
	v_exp_f32_e32 v130, v130
	v_exp_f32_e32 v131, v131
	v_mfma_f32_32x32x16_bf16 v[82:97], v[200:203], v[150:153], v[82:97]
	v_exp_f32_e32 v132, v132
	v_exp_f32_e32 v133, v133
	v_add_f32_e32 v204, v130, v131
	ds_read_b64_tr_b16 v[146:147], v195 offset:16384
	ds_read_b64_tr_b16 v[148:149], v195 offset:18432
	ds_read_b64_tr_b16 v[150:151], v195 offset:20480
	ds_read_b64_tr_b16 v[152:153], v195 offset:22528
	s_waitcnt lgkmcnt(4)
	v_mfma_f32_32x32x16_bf16 v[66:81], v[196:199], v[154:157], v[66:81]
	v_exp_f32_e32 v134, v134
	v_exp_f32_e32 v135, v135
	v_add_f32_e32 v204, v132, v204
	v_add_f32_e32 v204, v133, v204
	v_mfma_f32_32x32x16_bf16 v[66:81], v[200:203], v[158:161], v[66:81]
	v_exp_f32_e32 v136, v136
	v_exp_f32_e32 v137, v137
	v_add_f32_e32 v204, v134, v204
	v_add_f32_e32 v204, v135, v204
	ds_read_b64_tr_b16 v[154:155], v195 offset:16896
	ds_read_b64_tr_b16 v[156:157], v195 offset:18944
	ds_read_b64_tr_b16 v[158:159], v195 offset:20992
	ds_read_b64_tr_b16 v[160:161], v195 offset:23040
	s_waitcnt lgkmcnt(4)
; #define SBAR() __builtin_amdgcn_sched_barrier(0)
; __device__ __forceinline__ void finishSM(f32x16& p0, f32x16& p1, float alpha, float& l_reg, bf16x8& pa0, bf16x8& pa1, bf16x8& pa2, bf16x8& pa3) {
; #pragma unroll
;   for (int r = 0; r < 16; ++r) p1[r] = __builtin_amdgcn_exp2f(p1[r]);
;   float ps = 0;
; #pragma unroll
;   for (int r = 0; r < 16; ++r) ps += p0[r];
; #pragma unroll
;   for (int r = 0; r < 16; ++r) ps += p1[r];
;   { auto rr = __builtin_amdgcn_permlane32_swap(__float_as_uint(ps), __float_as_uint(ps), false, false);
;     ps = __uint_as_float(rr[0]) + __uint_as_float(rr[1]); }
;   l_reg = l_reg * alpha + ps;
;     ...
;   PK4(p0, 0, pa0); PK4(p0, 8, pa1); PK4(p1, 0, pa2); PK4(p1, 8, pa3);
;     ...
; }
; template <int D0> __device__ __forceinline__ void pv_one8(f32x16& od, int vb, bf16x8 pa0, bf16x8 pa1, bf16x8 pa2, bf16x8 pa3) {
;   constexpr int HB = (D0 >> 2) * 16384, DD = D0 & 3;
;   const s16x4 l0 = tr_read<HB + v_rd_off(DD, 0, 0)>(vb), h0 = tr_read<HB + v_rd_off(DD, 0, 1)>(vb), l1 = tr_read<HB + v_rd_off(DD, 1, 0)>(vb), h1 = tr_read<HB + v_rd_off(DD, 1, 1)>(vb);
;   const s16x4 l2 = tr_read<HB + v_rd_off(DD, 2, 0)>(vb), h2 = tr_read<HB + v_rd_off(DD, 2, 1)>(vb), l3 = tr_read<HB + v_rd_off(DD, 3, 0)>(vb), h3 = tr_read<HB + v_rd_off(DD, 3, 1)>(vb);
;   asm volatile("s_waitcnt lgkmcnt(0)" ::: "memory"); SBAR();
;     ...
;   od = __builtin_amdgcn_mfma_f32_32x32x16_bf16(pa0, PK(l0, h0), od, 0, 0, 0);
;   od = __builtin_amdgcn_mfma_f32_32x32x16_bf16(pa1, PK(l1, h1), od, 0, 0, 0);
;   od = __builtin_amdgcn_mfma_f32_32x32x16_bf16(pa2, PK(l2, h2), od, 0, 0, 0);
;   od = __builtin_amdgcn_mfma_f32_32x32x16_bf16(pa3, PK(l3, h3), od, 0, 0, 0);
	v_mfma_f32_32x32x16_bf16 v[50:65], v[196:199], v[146:149], v[50:65]
	v_exp_f32_e32 v138, v138
	v_exp_f32_e32 v139, v139
	v_add_f32_e32 v204, v136, v204
	v_add_f32_e32 v204, v137, v204
	v_mfma_f32_32x32x16_bf16 v[50:65], v[200:203], v[150:153], v[50:65]
	v_exp_f32_e32 v140, v140
	v_exp_f32_e32 v141, v141
	v_add_f32_e32 v204, v138, v204
	v_add_f32_e32 v204, v139, v204
	v_cvt_pk_bf16_f32 v130, v130, v131
	ds_read_b64_tr_b16 v[146:147], v195 offset:17408
	ds_read_b64_tr_b16 v[148:149], v195 offset:19456
	ds_read_b64_tr_b16 v[150:151], v195 offset:21504
	ds_read_b64_tr_b16 v[152:153], v195 offset:23552
	s_waitcnt lgkmcnt(4)
	v_mfma_f32_32x32x16_bf16 v[34:49], v[196:199], v[154:157], v[34:49]
	v_exp_f32_e32 v142, v142
	v_exp_f32_e32 v143, v143
	v_add_f32_e32 v204, v140, v204
	v_add_f32_e32 v204, v141, v204
	v_cvt_pk_bf16_f32 v131, v132, v133
	v_mfma_f32_32x32x16_bf16 v[34:49], v[200:203], v[158:161], v[34:49]
	v_exp_f32_e32 v144, v144
	v_exp_f32_e32 v145, v145
	v_add_f32_e32 v204, v142, v204
	v_add_f32_e32 v204, v143, v204
	v_cvt_pk_bf16_f32 v132, v134, v135
	ds_read_b64_tr_b16 v[154:155], v195 offset:17920
	ds_read_b64_tr_b16 v[156:157], v195 offset:19968
	ds_read_b64_tr_b16 v[158:159], v195 offset:22016
	ds_read_b64_tr_b16 v[160:161], v195 offset:24064
	s_waitcnt lgkmcnt(4)
	v_mfma_f32_32x32x16_bf16 v[18:33], v[196:199], v[146:149], v[18:33]
	v_cvt_pk_bf16_f32 v133, v136, v137
	v_cvt_pk_bf16_f32 v134, v138, v139
	v_add_f32_e32 v204, v144, v204
	v_add_f32_e32 v204, v145, v204
	v_mfma_f32_32x32x16_bf16 v[18:33], v[200:203], v[150:153], v[18:33]
	v_cvt_pk_bf16_f32 v135, v140, v141
	v_cvt_pk_bf16_f32 v136, v142, v143
	v_cvt_pk_bf16_f32 v137, v144, v145
	v_add_f32_e32 v204, v205, v204
	ds_read_b64_tr_b16 v[146:147], v195 offset:8192
	ds_read_b64_tr_b16 v[148:149], v195 offset:10240
	ds_read_b64_tr_b16 v[150:151], v195 offset:12288
	ds_read_b64_tr_b16 v[152:153], v195 offset:14336
	s_waitcnt lgkmcnt(4)
	v_mfma_f32_32x32x16_bf16 v[2:17], v[196:199], v[154:157], v[2:17]
	v_mov_b32_e32 v206, v204
	v_permlane32_swap_b32_e32 v130, v132
	v_permlane32_swap_b32_e32 v131, v133
	v_mfma_f32_32x32x16_bf16 v[2:17], v[200:203], v[158:161], v[2:17]
	v_permlane32_swap_b32_e32 v134, v136
	v_permlane32_swap_b32_e32 v135, v137
	v_permlane32_swap_b32_e32 v204, v206
	v_add_f32_e32 v248, v204, v206
	v_fmac_f32_e32 v248, v247, v0
	v_mov_b32_e32 v247, v248
	ds_read_b64_tr_b16 v[154:155], v195 offset:8704
	ds_read_b64_tr_b16 v[156:157], v195 offset:10752
	ds_read_b64_tr_b16 v[158:159], v195 offset:12800
	ds_read_b64_tr_b16 v[160:161], v195 offset:14848
	s_waitcnt lgkmcnt(4)
	v_mfma_f32_32x32x16_bf16 v[114:129], v[130:133], v[146:149], v[114:129]
	v_mfma_f32_32x32x16_bf16 v[114:129], v[134:137], v[150:153], v[114:129]
	ds_read_b64_tr_b16 v[146:147], v195 offset:9216
	ds_read_b64_tr_b16 v[148:149], v195 offset:11264
	ds_read_b64_tr_b16 v[150:151], v195 offset:13312
	ds_read_b64_tr_b16 v[152:153], v195 offset:15360
	s_waitcnt lgkmcnt(4)
	v_mfma_f32_32x32x16_bf16 v[98:113], v[130:133], v[154:157], v[98:113]
	v_mfma_f32_32x32x16_bf16 v[98:113], v[134:137], v[158:161], v[98:113]
	ds_read_b64_tr_b16 v[154:155], v195 offset:9728
	ds_read_b64_tr_b16 v[156:157], v195 offset:11776
	ds_read_b64_tr_b16 v[158:159], v195 offset:13824
	ds_read_b64_tr_b16 v[160:161], v195 offset:15872
	s_waitcnt lgkmcnt(4)
	v_mfma_f32_32x32x16_bf16 v[82:97], v[130:133], v[146:149], v[82:97]
	v_mfma_f32_32x32x16_bf16 v[82:97], v[134:137], v[150:153], v[82:97]
	ds_read_b64_tr_b16 v[146:147], v195 offset:24576
	ds_read_b64_tr_b16 v[148:149], v195 offset:26624
	ds_read_b64_tr_b16 v[150:151], v195 offset:28672
	ds_read_b64_tr_b16 v[152:153], v195 offset:30720
	s_waitcnt lgkmcnt(4)
	v_mfma_f32_32x32x16_bf16 v[66:81], v[130:133], v[154:157], v[66:81]
	v_mfma_f32_32x32x16_bf16 v[66:81], v[134:137], v[158:161], v[66:81]
	ds_read_b64_tr_b16 v[154:155], v195 offset:25088
	ds_read_b64_tr_b16 v[156:157], v195 offset:27136
	ds_read_b64_tr_b16 v[158:159], v195 offset:29184
	ds_read_b64_tr_b16 v[160:161], v195 offset:31232
	s_waitcnt lgkmcnt(4)
	v_mfma_f32_32x32x16_bf16 v[50:65], v[130:133], v[146:149], v[50:65]
	v_mfma_f32_32x32x16_bf16 v[50:65], v[134:137], v[150:153], v[50:65]
	ds_read_b64_tr_b16 v[146:147], v195 offset:25600
	ds_read_b64_tr_b16 v[148:149], v195 offset:27648
	ds_read_b64_tr_b16 v[150:151], v195 offset:29696
	ds_read_b64_tr_b16 v[152:153], v195 offset:31744
	s_waitcnt lgkmcnt(4)
	v_mfma_f32_32x32x16_bf16 v[34:49], v[130:133], v[154:157], v[34:49]
	v_mfma_f32_32x32x16_bf16 v[34:49], v[134:137], v[158:161], v[34:49]
	ds_read_b64_tr_b16 v[154:155], v195 offset:26112
	ds_read_b64_tr_b16 v[156:157], v195 offset:28160
	ds_read_b64_tr_b16 v[158:159], v195 offset:30208
	ds_read_b64_tr_b16 v[160:161], v195 offset:32256
	s_waitcnt lgkmcnt(4)
	v_mfma_f32_32x32x16_bf16 v[18:33], v[130:133], v[146:149], v[18:33]
	v_mfma_f32_32x32x16_bf16 v[18:33], v[134:137], v[150:153], v[18:33]
	s_waitcnt lgkmcnt(0)
	v_mfma_f32_32x32x16_bf16 v[2:17], v[130:133], v[154:157], v[2:17]
	v_mfma_f32_32x32x16_bf16 v[2:17], v[134:137], v[158:161], v[2:17]
